# v17 + non-temporal stores for the chain outputs in mixscan (keep Z lines in the memory-side cache for the opposite-direction chains)
# baseline (speedup 1.0000x reference)
.LBB0_508:
	v_add_u32_e32 v109, v72, v64
	v_add_u32_e32 v108, v73, v64
	ds_read_b64_tr_b16 v[40:41], v104 offset:27648
	ds_read_b64_tr_b16 v[42:43], v104 offset:28224
	v_exp_f32_e32 v60, v118
	v_exp_f32_e32 v61, v119
	ds_read_b128 v[44:47], v109 offset:36864
	v_exp_f32_e32 v62, v120
	v_exp_f32_e32 v63, v121
	ds_read_b128 v[36:39], v108 offset:36864
	s_waitcnt lgkmcnt(1)
	v_mfma_f32_16x16x32_bf16 v[44:47], v[40:43], v[44:47], 0
	ds_read_b64_tr_b16 v[48:49], v104 offset:18432
	ds_read_b64_tr_b16 v[50:51], v104 offset:19008
	ds_read_b64_tr_b16 v[52:53], v104 offset:32256
	v_pk_mul_f32 v[30:31], v[30:31], v[62:63]
	v_pk_mul_f32 v[28:29], v[28:29], v[60:61]
	s_waitcnt lgkmcnt(3)
	v_mfma_f32_16x16x32_bf16 v[36:39], v[40:43], v[36:39], 0
	ds_read_b64_tr_b16 v[40:41], v106 offset:27648
	ds_read_b64_tr_b16 v[42:43], v106 offset:28224
	ds_read_b64_tr_b16 v[56:57], v107 offset:27648
	ds_read_b64_tr_b16 v[58:59], v107 offset:28224
	ds_read_b64_tr_b16 v[54:55], v104 offset:32832
	v_pk_mul_f32 v[34:35], v[34:35], v[62:63]
	v_pk_mul_f32 v[32:33], v[32:33], v[60:61]
	s_waitcnt lgkmcnt(3)
	v_mfma_f32_16x16x32_bf16 v[28:31], v[48:51], v[40:43], v[28:31]
	v_add_u32_e32 v113, v72, v74
	v_add_u32_e32 v112, v73, v74
	v_readlane_b32 s4, v255, 10
	s_waitcnt lgkmcnt(1)
	v_mfma_f32_16x16x32_bf16 v[40:43], v[48:51], v[56:59], v[32:35]
	s_nop 2
	ds_read_b128 v[32:35], v109 offset:36928
	ds_read_b64_tr_b16 v[48:49], v104 offset:23616
	ds_read_b128 v[56:59], v108 offset:36928
	s_and_b64 vcc, exec, s[34:35]
	s_waitcnt lgkmcnt(2)
	v_mfma_f32_16x16x32_bf16 v[60:63], v[52:55], v[32:35], v[44:47]
	s_nop 2
	ds_read_b64_tr_b16 v[46:47], v104 offset:23040
	ds_read_b64_tr_b16 v[32:33], v106 offset:32256
	s_waitcnt lgkmcnt(2)
	v_mfma_f32_16x16x32_bf16 v[36:39], v[52:55], v[56:59], v[36:39]
	ds_read_b64_tr_b16 v[34:35], v106 offset:32832
	ds_read_b64_tr_b16 v[50:51], v107 offset:32256
	ds_read_b64_tr_b16 v[52:53], v107 offset:32832
	ds_read_b128 v[54:57], v105 offset:46080
	s_waitcnt lgkmcnt(3)
	v_mfma_f32_16x16x32_bf16 v[32:35], v[46:49], v[32:35], v[28:31]
	s_waitcnt lgkmcnt(1)
	v_mfma_f32_16x16x32_bf16 v[28:31], v[46:49], v[50:53], v[40:43]
	s_nop 2
	ds_read_b128 v[40:43], v109 offset:9216
	ds_read_b128 v[44:47], v108 offset:9216
	ds_read_b128 v[48:51], v105 offset:46144
	s_waitcnt lgkmcnt(1)
	v_mfma_f32_16x16x32_bf16 v[36:39], v[54:57], v[44:47], v[36:39]
	ds_read_b128 v[44:47], v109 offset:9280
	v_mfma_f32_16x16x32_bf16 v[40:43], v[54:57], v[40:43], v[60:63]
	s_waitcnt lgkmcnt(0)
	v_mfma_f32_16x16x32_bf16 v[40:43], v[48:51], v[44:47], v[40:43]
	ds_read_b128 v[44:47], v108 offset:9280
	s_waitcnt lgkmcnt(0)
	v_mfma_f32_16x16x32_bf16 v[36:39], v[48:51], v[44:47], v[36:39]
	v_cvt_pk_bf16_f32 v44, v32, v33
	v_cvt_pk_bf16_f32 v45, v34, v35
	ds_write_b64 v113, v[44:45] offset:55296
	v_cvt_pk_bf16_f32 v44, v28, v29
	v_cvt_pk_bf16_f32 v45, v30, v31
	ds_write_b64 v112, v[44:45] offset:55296
	v_add_u32_e32 v44, s48, v75
	v_lshl_or_b32 v180, v44, 10, v76
	v_cvt_pk_bf16_f32 v40, v40, v41
	v_cvt_pk_bf16_f32 v41, v42, v43
	v_lshl_add_u64 v[42:43], v[180:181], 1, s[92:93]
	global_store_dwordx2 v[42:43], v[40:41], off nt
	v_add_u32_e32 v40, s48, v77
	v_lshl_or_b32 v180, v40, 10, v76
	v_cvt_pk_bf16_f32 v36, v36, v37
	v_cvt_pk_bf16_f32 v37, v38, v39
	v_lshl_add_u64 v[38:39], v[180:181], 1, s[92:93]
	global_store_dwordx2 v[38:39], v[36:37], off nt
	v_mov_b32_e32 v36, v68
	s_waitcnt lgkmcnt(0)
	s_barrier
	v_mov_b32_e32 v43, 0
	v_lshrrev_b32_e32 v37, 3, v36
	v_and_or_b32 v40, v37, 7, s70
	v_and_b32_e32 v41, 7, v36
	v_lshlrev_b32_e32 v36, 8, v40
	v_lshlrev_b32_e32 v37, 5, v41
	v_add3_u32 v36, s4, v36, v37
	ds_read_b128 v[44:47], v36
	ds_read_b128 v[36:39], v36 offset:16
	v_mul_lo_u32 v116, v40, s72
	v_lshlrev_b32_e32 v117, 4, v41
	v_lshlrev_b32_e32 v115, 3, v41
	v_add3_u32 v114, 0, v116, v117
	v_mov_b32_e32 v42, 0
	v_mov_b32_e32 v41, 0
	v_mov_b32_e32 v40, 0
	v_mov_b32_e32 v51, 0
	v_mov_b32_e32 v50, 0
	v_mov_b32_e32 v49, 0
	v_mov_b32_e32 v48, 0
	s_waitcnt vmcnt(9)
	ds_write_b128 v114, v[24:27] offset:27648
	s_cbranch_vccnz .LBB0_510
	v_lshl_add_u32 v40, v115, 2, s62
	ds_read_b128 v[48:51], v40
	ds_read_b128 v[40:43], v40 offset:16
